# opt43: opt41 + diff-attention loop: tile a's eight K-fragment LDS reads issued at the top of the iteration, ahead of the scalar classification block
# baseline (speedup 1.0000x reference)
; #define DMA_T(s_) do { DMA_K(s_); DMA_V(s_); } while (0)
; #define CLASSIFY(kv0_, act_, cls_) do { act_ = true; if (SWA) act_ = ((kv0_) + 63 >= qw - 128) && ((kv0_) <= qw + 159); \
;         cls_ = 0; if ((kv0_) + 63 < qw) cls_ = 1; else if ((kv0_) > qw + 31) cls_ = 2; \
;         if (SWA) { if (cls_ == 1 && qw + 31 - (kv0_) > 128) cls_ = 0; if (cls_ == 2 && (kv0_) + 63 - qw > 128) cls_ = 0; } } while (0)
; template <bool SWA>
; __device__ __forceinline__ void unit(LAS unsigned char* lds, const bf16_t* PROJ, const bf16_t* KT, const bf16_t* VT, bf16_t* OB, int opitch, int ocol, int b, int head, int qb, float slope2, float m_init, float lam, const float* subg) {
;     ...
;     for (int S = 0; S < npairs; ++S) {
;         const int sa = 2 * S, sb = 2 * S + 1;
;         if (sa + 2 < nsteps) DMA_T(sa + 2);
;         if (sb + 2 < nsteps) DMA_T(sb + 2);
;         const int kva = TILE_OF(sa) * 64, kvb = TILE_OF(sb < nsteps ? sb : sa) * 64;
;         bool acta, actb; int clsa, clsb;
;         CLASSIFY(kva, acta, clsa); CLASSIFY(kvb, actb, clsb); actb = actb && (sb < nsteps);
.LBB0_884:
	s_add_i32 s93, s25, 0xffff4000
	s_and_b32 s93, s93, 0x8000
	v_add_u32_e32 v65, s93, v199
	ds_read_b128 v[66:69], v65
	ds_read_b128 v[70:73], v65 offset:8192
	v_add_u32_e32 v65, s93, v200
	ds_read_b128 v[74:77], v65
	ds_read_b128 v[78:81], v65 offset:8192
	v_add_u32_e32 v65, s93, v201
	ds_read_b128 v[82:85], v65
	ds_read_b128 v[86:89], v65 offset:8192
	v_add_u32_e32 v65, s93, v202
	ds_read_b128 v[90:93], v65
	ds_read_b128 v[204:207], v65 offset:8192
	s_add_i32 s29, s1, -3
	s_add_i32 s27, s1, -2
	s_add_i32 s6, s1, -1
	s_cmp_lt_u32 s29, s0
	s_cselect_b32 s6, s29, s6
	s_mov_b32 s28, s26
	s_lshl_b32 s26, s6, 14
	s_cmp_lt_u32 s27, s0
	s_cselect_b32 s6, s27, s1
	s_lshl_b32 s26, s6, 14
	s_add_u32 s98, s73, s26
	s_addc_u32 s99, s17, 0
	s_add_u32 s100, s2, s26
	s_addc_u32 s101, s23, 0
	s_and_b32 s30, s25, 0xc000
	s_add_i32 s32, s30, s33
	s_add_i32 s71, s30, s72
	s_add_i32 s26, s28, 0x80
	s_cmp_gt_u32 s29, s0
	s_cselect_b64 s[78:79], -1, 0
	s_and_b64 s[6:7], s[78:79], exec
	s_cselect_b32 s30, s26, s28
	s_or_b32 s28, s30, 63
	s_cmp_ge_i32 s28, s5
	s_cselect_b64 s[6:7], -1, 0
	s_cmp_lt_i32 s28, s5
	s_cselect_b64 s[82:83], -1, 0
	s_cmp_le_i32 s30, s19
	s_cselect_b64 s[80:81], -1, 0
	s_and_b64 s[84:85], s[6:7], s[80:81]
	s_and_b64 vcc, exec, s[84:85]
	v_mov_b32_e32 v64, 0
	s_cbranch_vccnz .LBB0_886
	s_and_b64 s[28:29], s[80:81], exec
	s_cselect_b32 s28, 0, 64
	s_and_b64 s[6:7], s[6:7], exec
	s_cselect_b32 s6, s28, 0
	s_add_i32 s6, s6, 0
	s_add_i32 s6, s6, 0x20200
	v_mov_b32_e32 v65, s6
	ds_read_b128 v[96:99], v65
	ds_read_b128 v[100:103], v65 offset:16
	ds_read_b128 v[104:107], v65 offset:32
	ds_read_b128 v[108:111], v65 offset:48
	s_branch .LBB0_887

.LBB0_887:
	s_add_i32 s28, s1, -4
	s_and_b64 s[6:7], s[78:79], exec
	s_cselect_b32 s6, s27, s28
	s_lshl_b32 s28, s6, 6
	s_or_b32 s6, s28, 63
	s_cmp_ge_i32 s6, s5
	s_cselect_b64 s[86:87], -1, 0
	s_cmp_lt_i32 s6, s5
	s_cselect_b64 s[78:79], -1, 0
	s_cmp_le_i32 s28, s19
	s_cselect_b64 s[88:89], -1, 0
	s_add_i32 s6, s25, 0xffff4000
	s_and_b32 s6, s6, 0x8000
	s_add_i32 s29, s6, 0
	s_and_b64 s[80:81], s[86:87], s[88:89]
	s_setprio 1
	s_waitcnt lgkmcnt(0)
	v_mfma_f32_32x32x16_bf16 v[112:127], v[66:69], v[140:143], v[96:111]
	s_waitcnt lgkmcnt(6)
	v_mfma_f32_32x32x16_bf16 v[96:111], v[70:73], v[140:143], v[96:111]
	s_waitcnt lgkmcnt(5)
	v_mfma_f32_32x32x16_bf16 v[112:127], v[74:77], v[136:139], v[112:127]
	s_waitcnt lgkmcnt(4)
	v_mfma_f32_32x32x16_bf16 v[96:111], v[78:81], v[136:139], v[96:111]
	s_waitcnt lgkmcnt(3)
	v_mfma_f32_32x32x16_bf16 v[112:127], v[82:85], v[132:135], v[112:127]
	s_waitcnt lgkmcnt(2)
	v_mfma_f32_32x32x16_bf16 v[96:111], v[86:89], v[132:135], v[96:111]
	s_waitcnt lgkmcnt(1)
	v_mfma_f32_32x32x16_bf16 v[112:127], v[90:93], v[128:131], v[112:127]
	s_waitcnt lgkmcnt(0)
	v_mfma_f32_32x32x16_bf16 v[96:111], v[204:207], v[128:131], v[96:111]
	s_setprio 0
	s_mov_b32 m0, s32
	s_nop 0
	global_load_lds_dwordx4 v164, s[98:99]
	s_add_i32 m0, s32, 0x400
	s_nop 0
	global_load_lds_dwordx4 v170, s[98:99]
	s_and_b64 vcc, exec, s[80:81]
	v_mov_b32_e32 v65, 0
	v_mov_b32_e32 v66, 0
	v_mov_b32_e32 v67, 0
	v_mov_b32_e32 v68, 0
	v_mov_b32_e32 v69, 0
	v_mov_b32_e32 v70, 0
	v_mov_b32_e32 v71, 0
	v_mov_b32_e32 v72, 0
	v_mov_b32_e32 v73, 0
	v_mov_b32_e32 v74, 0
	v_mov_b32_e32 v75, 0
	v_mov_b32_e32 v76, 0
	v_mov_b32_e32 v77, 0
	v_mov_b32_e32 v78, 0
	v_mov_b32_e32 v79, 0
	s_cbranch_vccnz .LBB0_889
	s_and_b64 s[6:7], s[88:89], exec
	s_cselect_b32 s27, 0, 64
	s_and_b64 s[6:7], s[86:87], exec
	s_cselect_b32 s6, s27, 0
	s_add_i32 s6, s6, 0
	s_add_i32 s6, s6, 0x20200
	v_mov_b32_e32 v76, s6
	ds_read_b128 v[64:67], v76
	ds_read_b128 v[68:71], v76 offset:16
	ds_read_b128 v[72:75], v76 offset:32
	ds_read_b128 v[76:79], v76 offset:48
